# hand-written epilogue of the FFN-down main GEMM: permlane16_swap pairs the n=0/n=1 fragments so each lane owns 8 consecutive columns, dwordx4 residual loads and stores (16+16 instead of 32+32 dwordx2)
# speedup vs baseline: 1.0110x; 1.0076x over previous
; __device__ __forceinline__ unsigned cvt_pk_bf16(float lo, float hi) { unsigned r; asm("v_cvt_pk_bf16_f32 %0, %1, %2" : "=v"(r) : "v"(lo), "v"(hi)); return r; }
; __device__ __forceinline__ f32x4 ld_bf4(const bf16_t* p) { const u32x2 w = *(const u32x2*)p; return (f32x4){bf_lo(w.x), bf_hi(w.x), bf_lo(w.y), bf_hi(w.y)}; }
;     __device__ __forceinline__ void operator()(const f32x4 (&acc)[2][2][4][2], const pg8::Unit& u, int wr, int wc, int fr, int fq) const {
;         const int row0 = u.pm * 256 + wr * 64 + fr, col0 = u.pn * 256 + wc * 32 + 4 * fq;
;         f32x4 swv[2][2];
; #pragma unroll
;         for (int bj = 0; bj < 2; ++bj)
; #pragma unroll
;             for (int n = 0; n < 2; ++n) swv[bj][n] = *(const f32x4*)(sw + col0 + bj * 128 + n * 16);
;         float sav[2][4];
; #pragma unroll
;         for (int ai = 0; ai < 2; ++ai)
; #pragma unroll
;             for (int m = 0; m < 4; ++m) sav[ai][m] = sa[row0 + ai * 128 + m * 16];
; #pragma unroll
;         for (int am = 0; am < 4; ++am) { const int ai = am >> 1, m0 = 2 * (am & 1); f32x4 r[2][2][2];
; #pragma unroll
;             for (int mm = 0; mm < 2; ++mm) { const size_t off = (size_t)(row0 + ai * 128 + (m0 + mm) * 16) * DM + col0;
; #pragma unroll
;                 for (int bj = 0; bj < 2; ++bj)
; #pragma unroll
;                     for (int n = 0; n < 2; ++n) r[mm][bj][n] = ld_bf4(X1 + off + bj * 128 + n * 16); }
; #pragma unroll
;             for (int mm = 0; mm < 2; ++mm) { const size_t off = (size_t)(row0 + ai * 128 + (m0 + mm) * 16) * DM + col0;
; #pragma unroll
;                 for (int bj = 0; bj < 2; ++bj)
; #pragma unroll
;                     for (int n = 0; n < 2; ++n) { const i32x4 q = __builtin_bit_cast(i32x4, acc[ai][bj][m0 + mm][n]);
;                         const f32x4 v = (f32x4){(float)q[0], (float)q[1], (float)q[2], (float)q[3]} * swv[bj][n] * sav[ai][m0 + mm] + r[mm][bj][n];
;                         u32x2 w; w.x = cvt_pk_bf16(v[0], v[1]); w.y = cvt_pk_bf16(v[2], v[3]); *(u32x2*)(X2 + off + bj * 128 + n * 16) = w; } } }
;     }
.LBB0_2875:
	v_lshl_add_u32 v182, s58, 8, v173
	v_and_b32_e32 v183, 1, v235
	v_mul_u32_u24_e32 v183, 12, v183
	v_add_u32_e32 v183, v183, v179
	v_lshl_or_b32 v183, s59, 8, v183
	v_lshlrev_b32_e32 v152, 2, v182
	v_lshlrev_b32_e32 v153, 2, v183
	v_lshlrev_b32_e32 v154, 13, v182
	v_lshl_add_u32 v154, v183, 1, v154
	global_load_dword v160, v152, s[8:9] offset:0
	global_load_dword v161, v152, s[8:9] offset:64
	global_load_dword v162, v152, s[8:9] offset:128
	global_load_dword v163, v152, s[8:9] offset:192
	global_load_dword v164, v152, s[8:9] offset:512
	global_load_dword v166, v152, s[8:9] offset:576
	global_load_dword v167, v152, s[8:9] offset:640
	global_load_dword v168, v152, s[8:9] offset:704
	global_load_dwordx4 v[184:187], v153, s[10:11] offset:0
	global_load_dwordx4 v[188:191], v153, s[10:11] offset:16
	global_load_dwordx4 v[192:195], v153, s[10:11] offset:512
	global_load_dwordx4 v[196:199], v153, s[10:11] offset:528
	v_mov_b32_e32 v156, v154
	global_load_dwordx4 v[200:203], v156, s[16:17] offset:0
	v_mov_b32_e32 v157, v154
	global_load_dwordx4 v[208:211], v157, s[16:17] offset:256
	v_add_u32_e32 v156, 0x20000, v154
	global_load_dwordx4 v[212:215], v156, s[16:17] offset:0
	v_add_u32_e32 v157, 0x20000, v154
	global_load_dwordx4 v[216:219], v157, s[16:17] offset:256
	v_add_u32_e32 v156, 0x40000, v154
	global_load_dwordx4 v[220:223], v156, s[16:17] offset:0
	v_add_u32_e32 v157, 0x40000, v154
	global_load_dwordx4 v[224:227], v157, s[16:17] offset:256
	v_add_u32_e32 v156, 0x60000, v154
	global_load_dwordx4 v[228:231], v156, s[16:17] offset:0
	v_add_u32_e32 v157, 0x60000, v154
	global_load_dwordx4 v[98:101], v157, s[16:17] offset:256
	v_permlane16_swap_b32_e32 v94, v138
	v_permlane16_swap_b32_e32 v95, v139
	v_permlane16_swap_b32_e32 v96, v140
	v_permlane16_swap_b32_e32 v97, v141
	v_cvt_f32_i32_e32 v94, v94
	v_cvt_f32_i32_e32 v95, v95
	v_cvt_f32_i32_e32 v96, v96
	v_cvt_f32_i32_e32 v97, v97
	v_cvt_f32_i32_e32 v138, v138
	v_cvt_f32_i32_e32 v139, v139
	v_cvt_f32_i32_e32 v140, v140
	v_cvt_f32_i32_e32 v141, v141
	s_waitcnt vmcnt(7)
	v_pk_mul_f32 v[94:95], v[94:95], v[184:185]
	v_pk_mul_f32 v[96:97], v[96:97], v[186:187]
	v_pk_mul_f32 v[138:139], v[138:139], v[188:189]
	v_pk_mul_f32 v[140:141], v[140:141], v[190:191]
	v_lshlrev_b32_e32 v102, 16, v200
	v_and_b32_e32 v200, 0xffff0000, v200
	v_lshlrev_b32_e32 v103, 16, v201
	v_and_b32_e32 v201, 0xffff0000, v201
	v_lshlrev_b32_e32 v104, 16, v202
	v_and_b32_e32 v202, 0xffff0000, v202
	v_lshlrev_b32_e32 v105, 16, v203
	v_and_b32_e32 v203, 0xffff0000, v203
	v_fma_f32 v94, v94, v160, v102
	v_fma_f32 v95, v95, v160, v200
	v_fma_f32 v96, v96, v160, v103
	v_fma_f32 v97, v97, v160, v201
	v_fma_f32 v138, v138, v160, v104
	v_fma_f32 v139, v139, v160, v202
	v_fma_f32 v140, v140, v160, v105
	v_fma_f32 v141, v141, v160, v203
	v_cvt_pk_bf16_f32 v94, v94, v95
	v_cvt_pk_bf16_f32 v95, v96, v97
	v_cvt_pk_bf16_f32 v96, v138, v139
	v_cvt_pk_bf16_f32 v97, v140, v141
	v_permlane16_swap_b32_e32 v134, v126
	v_permlane16_swap_b32_e32 v135, v127
	v_permlane16_swap_b32_e32 v136, v128
	v_permlane16_swap_b32_e32 v137, v129
	v_cvt_f32_i32_e32 v134, v134
	v_cvt_f32_i32_e32 v135, v135
	v_cvt_f32_i32_e32 v136, v136
	v_cvt_f32_i32_e32 v137, v137
	v_cvt_f32_i32_e32 v126, v126
	v_cvt_f32_i32_e32 v127, v127
	v_cvt_f32_i32_e32 v128, v128
	v_cvt_f32_i32_e32 v129, v129
	s_waitcnt vmcnt(6)
	v_pk_mul_f32 v[134:135], v[134:135], v[192:193]
	v_pk_mul_f32 v[136:137], v[136:137], v[194:195]
	v_pk_mul_f32 v[126:127], v[126:127], v[196:197]
	v_pk_mul_f32 v[128:129], v[128:129], v[198:199]
	v_lshlrev_b32_e32 v102, 16, v208
	v_and_b32_e32 v208, 0xffff0000, v208
	v_lshlrev_b32_e32 v103, 16, v209
	v_and_b32_e32 v209, 0xffff0000, v209
	v_lshlrev_b32_e32 v104, 16, v210
	v_and_b32_e32 v210, 0xffff0000, v210
	v_lshlrev_b32_e32 v105, 16, v211
	v_and_b32_e32 v211, 0xffff0000, v211
	v_fma_f32 v134, v134, v160, v102
	v_fma_f32 v135, v135, v160, v208
	v_fma_f32 v136, v136, v160, v103
	v_fma_f32 v137, v137, v160, v209
	v_fma_f32 v126, v126, v160, v104
	v_fma_f32 v127, v127, v160, v210
	v_fma_f32 v128, v128, v160, v105
	v_fma_f32 v129, v129, v160, v211
	v_cvt_pk_bf16_f32 v134, v134, v135
	v_cvt_pk_bf16_f32 v135, v136, v137
	v_cvt_pk_bf16_f32 v136, v126, v127
	v_cvt_pk_bf16_f32 v137, v128, v129
	v_permlane16_swap_b32_e32 v130, v122
	v_permlane16_swap_b32_e32 v131, v123
	v_permlane16_swap_b32_e32 v132, v124
	v_permlane16_swap_b32_e32 v133, v125
	v_cvt_f32_i32_e32 v130, v130
	v_cvt_f32_i32_e32 v131, v131
	v_cvt_f32_i32_e32 v132, v132
	v_cvt_f32_i32_e32 v133, v133
	v_cvt_f32_i32_e32 v122, v122
	v_cvt_f32_i32_e32 v123, v123
	v_cvt_f32_i32_e32 v124, v124
	v_cvt_f32_i32_e32 v125, v125
	s_waitcnt vmcnt(5)
	v_pk_mul_f32 v[130:131], v[130:131], v[184:185]
	v_pk_mul_f32 v[132:133], v[132:133], v[186:187]
	v_pk_mul_f32 v[122:123], v[122:123], v[188:189]
	v_pk_mul_f32 v[124:125], v[124:125], v[190:191]
	v_lshlrev_b32_e32 v102, 16, v212
	v_and_b32_e32 v212, 0xffff0000, v212
	v_lshlrev_b32_e32 v103, 16, v213
	v_and_b32_e32 v213, 0xffff0000, v213
	v_lshlrev_b32_e32 v104, 16, v214
	v_and_b32_e32 v214, 0xffff0000, v214
	v_lshlrev_b32_e32 v105, 16, v215
	v_and_b32_e32 v215, 0xffff0000, v215
	v_fma_f32 v130, v130, v161, v102
	v_fma_f32 v131, v131, v161, v212
	v_fma_f32 v132, v132, v161, v103
	v_fma_f32 v133, v133, v161, v213
	v_fma_f32 v122, v122, v161, v104
	v_fma_f32 v123, v123, v161, v214
	v_fma_f32 v124, v124, v161, v105
	v_fma_f32 v125, v125, v161, v215
	v_cvt_pk_bf16_f32 v130, v130, v131
	v_cvt_pk_bf16_f32 v131, v132, v133
	v_cvt_pk_bf16_f32 v132, v122, v123
	v_cvt_pk_bf16_f32 v133, v124, v125
	v_permlane16_swap_b32_e32 v118, v114
	v_permlane16_swap_b32_e32 v119, v115
	v_permlane16_swap_b32_e32 v120, v116
	v_permlane16_swap_b32_e32 v121, v117
	v_cvt_f32_i32_e32 v118, v118
	v_cvt_f32_i32_e32 v119, v119
	v_cvt_f32_i32_e32 v120, v120
	v_cvt_f32_i32_e32 v121, v121
	v_cvt_f32_i32_e32 v114, v114
	v_cvt_f32_i32_e32 v115, v115
	v_cvt_f32_i32_e32 v116, v116
	v_cvt_f32_i32_e32 v117, v117
	s_waitcnt vmcnt(4)
; __device__ __forceinline__ unsigned cvt_pk_bf16(float lo, float hi) { unsigned r; asm("v_cvt_pk_bf16_f32 %0, %1, %2" : "=v"(r) : "v"(lo), "v"(hi)); return r; }
; __device__ __forceinline__ f32x4 ld_bf4(const bf16_t* p) { const u32x2 w = *(const u32x2*)p; return (f32x4){bf_lo(w.x), bf_hi(w.x), bf_lo(w.y), bf_hi(w.y)}; }
;     __device__ __forceinline__ void operator()(const f32x4 (&acc)[2][2][4][2], const pg8::Unit& u, int wr, int wc, int fr, int fq) const {
;         const int row0 = u.pm * 256 + wr * 64 + fr, col0 = u.pn * 256 + wc * 32 + 4 * fq;
;         f32x4 swv[2][2];
; #pragma unroll
;         for (int bj = 0; bj < 2; ++bj)
; #pragma unroll
;             for (int n = 0; n < 2; ++n) swv[bj][n] = *(const f32x4*)(sw + col0 + bj * 128 + n * 16);
;         float sav[2][4];
; #pragma unroll
;         for (int ai = 0; ai < 2; ++ai)
; #pragma unroll
;             for (int m = 0; m < 4; ++m) sav[ai][m] = sa[row0 + ai * 128 + m * 16];
; #pragma unroll
;         for (int am = 0; am < 4; ++am) { const int ai = am >> 1, m0 = 2 * (am & 1); f32x4 r[2][2][2];
; #pragma unroll
;             for (int mm = 0; mm < 2; ++mm) { const size_t off = (size_t)(row0 + ai * 128 + (m0 + mm) * 16) * DM + col0;
; #pragma unroll
;                 for (int bj = 0; bj < 2; ++bj)
; #pragma unroll
;                     for (int n = 0; n < 2; ++n) r[mm][bj][n] = ld_bf4(X1 + off + bj * 128 + n * 16); }
; #pragma unroll
;             for (int mm = 0; mm < 2; ++mm) { const size_t off = (size_t)(row0 + ai * 128 + (m0 + mm) * 16) * DM + col0;
; #pragma unroll
;                 for (int bj = 0; bj < 2; ++bj)
; #pragma unroll
;                     for (int n = 0; n < 2; ++n) { const i32x4 q = __builtin_bit_cast(i32x4, acc[ai][bj][m0 + mm][n]);
;                         const f32x4 v = (f32x4){(float)q[0], (float)q[1], (float)q[2], (float)q[3]} * swv[bj][n] * sav[ai][m0 + mm] + r[mm][bj][n];
;                         u32x2 w; w.x = cvt_pk_bf16(v[0], v[1]); w.y = cvt_pk_bf16(v[2], v[3]); *(u32x2*)(X2 + off + bj * 128 + n * 16) = w; } } }
;     }
	v_pk_mul_f32 v[118:119], v[118:119], v[192:193]
	v_pk_mul_f32 v[120:121], v[120:121], v[194:195]
	v_pk_mul_f32 v[114:115], v[114:115], v[196:197]
	v_pk_mul_f32 v[116:117], v[116:117], v[198:199]
	v_lshlrev_b32_e32 v102, 16, v216
	v_and_b32_e32 v216, 0xffff0000, v216
	v_lshlrev_b32_e32 v103, 16, v217
	v_and_b32_e32 v217, 0xffff0000, v217
	v_lshlrev_b32_e32 v104, 16, v218
	v_and_b32_e32 v218, 0xffff0000, v218
	v_lshlrev_b32_e32 v105, 16, v219
	v_and_b32_e32 v219, 0xffff0000, v219
	v_fma_f32 v118, v118, v161, v102
	v_fma_f32 v119, v119, v161, v216
	v_fma_f32 v120, v120, v161, v103
	v_fma_f32 v121, v121, v161, v217
	v_fma_f32 v114, v114, v161, v104
	v_fma_f32 v115, v115, v161, v218
	v_fma_f32 v116, v116, v161, v105
	v_fma_f32 v117, v117, v161, v219
	v_cvt_pk_bf16_f32 v118, v118, v119
	v_cvt_pk_bf16_f32 v119, v120, v121
	v_cvt_pk_bf16_f32 v120, v114, v115
	v_cvt_pk_bf16_f32 v121, v116, v117
	v_permlane16_swap_b32_e32 v110, v106
	v_permlane16_swap_b32_e32 v111, v107
	v_permlane16_swap_b32_e32 v112, v108
	v_permlane16_swap_b32_e32 v113, v109
	v_cvt_f32_i32_e32 v110, v110
	v_cvt_f32_i32_e32 v111, v111
	v_cvt_f32_i32_e32 v112, v112
	v_cvt_f32_i32_e32 v113, v113
	v_cvt_f32_i32_e32 v106, v106
	v_cvt_f32_i32_e32 v107, v107
	v_cvt_f32_i32_e32 v108, v108
	v_cvt_f32_i32_e32 v109, v109
	s_waitcnt vmcnt(3)
	v_pk_mul_f32 v[110:111], v[110:111], v[184:185]
	v_pk_mul_f32 v[112:113], v[112:113], v[186:187]
	v_pk_mul_f32 v[106:107], v[106:107], v[188:189]
	v_pk_mul_f32 v[108:109], v[108:109], v[190:191]
	v_lshlrev_b32_e32 v102, 16, v220
	v_and_b32_e32 v220, 0xffff0000, v220
	v_lshlrev_b32_e32 v103, 16, v221
	v_and_b32_e32 v221, 0xffff0000, v221
	v_lshlrev_b32_e32 v104, 16, v222
	v_and_b32_e32 v222, 0xffff0000, v222
	v_lshlrev_b32_e32 v105, 16, v223
	v_and_b32_e32 v223, 0xffff0000, v223
	v_fma_f32 v110, v110, v162, v102
	v_fma_f32 v111, v111, v162, v220
	v_fma_f32 v112, v112, v162, v103
	v_fma_f32 v113, v113, v162, v221
	v_fma_f32 v106, v106, v162, v104
	v_fma_f32 v107, v107, v162, v222
	v_fma_f32 v108, v108, v162, v105
	v_fma_f32 v109, v109, v162, v223
	v_cvt_pk_bf16_f32 v110, v110, v111
	v_cvt_pk_bf16_f32 v111, v112, v113
	v_cvt_pk_bf16_f32 v112, v106, v107
	v_cvt_pk_bf16_f32 v113, v108, v109
	v_permlane16_swap_b32_e32 v86, v78
	v_permlane16_swap_b32_e32 v87, v79
	v_permlane16_swap_b32_e32 v88, v80
	v_permlane16_swap_b32_e32 v89, v81
	v_cvt_f32_i32_e32 v86, v86
	v_cvt_f32_i32_e32 v87, v87
	v_cvt_f32_i32_e32 v88, v88
	v_cvt_f32_i32_e32 v89, v89
	v_cvt_f32_i32_e32 v78, v78
	v_cvt_f32_i32_e32 v79, v79
	v_cvt_f32_i32_e32 v80, v80
	v_cvt_f32_i32_e32 v81, v81
	s_waitcnt vmcnt(2)
	v_pk_mul_f32 v[86:87], v[86:87], v[192:193]
	v_pk_mul_f32 v[88:89], v[88:89], v[194:195]
	v_pk_mul_f32 v[78:79], v[78:79], v[196:197]
	v_pk_mul_f32 v[80:81], v[80:81], v[198:199]
	v_lshlrev_b32_e32 v102, 16, v224
	v_and_b32_e32 v224, 0xffff0000, v224
	v_lshlrev_b32_e32 v103, 16, v225
	v_and_b32_e32 v225, 0xffff0000, v225
	v_lshlrev_b32_e32 v104, 16, v226
	v_and_b32_e32 v226, 0xffff0000, v226
	v_lshlrev_b32_e32 v105, 16, v227
	v_and_b32_e32 v227, 0xffff0000, v227
	v_fma_f32 v86, v86, v162, v102
	v_fma_f32 v87, v87, v162, v224
	v_fma_f32 v88, v88, v162, v103
	v_fma_f32 v89, v89, v162, v225
	v_fma_f32 v78, v78, v162, v104
	v_fma_f32 v79, v79, v162, v226
	v_fma_f32 v80, v80, v162, v105
	v_fma_f32 v81, v81, v162, v227
	v_cvt_pk_bf16_f32 v86, v86, v87
	v_cvt_pk_bf16_f32 v87, v88, v89
	v_cvt_pk_bf16_f32 v88, v78, v79
	v_cvt_pk_bf16_f32 v89, v80, v81
	v_permlane16_swap_b32_e32 v82, v74
	v_permlane16_swap_b32_e32 v83, v75
	v_permlane16_swap_b32_e32 v84, v76
	v_permlane16_swap_b32_e32 v85, v77
	v_cvt_f32_i32_e32 v82, v82
	v_cvt_f32_i32_e32 v83, v83
	v_cvt_f32_i32_e32 v84, v84
	v_cvt_f32_i32_e32 v85, v85
	v_cvt_f32_i32_e32 v74, v74
	v_cvt_f32_i32_e32 v75, v75
	v_cvt_f32_i32_e32 v76, v76
	v_cvt_f32_i32_e32 v77, v77
	s_waitcnt vmcnt(1)
	v_pk_mul_f32 v[82:83], v[82:83], v[184:185]
	v_pk_mul_f32 v[84:85], v[84:85], v[186:187]
	v_pk_mul_f32 v[74:75], v[74:75], v[188:189]
	v_pk_mul_f32 v[76:77], v[76:77], v[190:191]
	v_lshlrev_b32_e32 v102, 16, v228
	v_and_b32_e32 v228, 0xffff0000, v228
	v_lshlrev_b32_e32 v103, 16, v229
	v_and_b32_e32 v229, 0xffff0000, v229
	v_lshlrev_b32_e32 v104, 16, v230
	v_and_b32_e32 v230, 0xffff0000, v230
	v_lshlrev_b32_e32 v105, 16, v231
	v_and_b32_e32 v231, 0xffff0000, v231
	v_fma_f32 v82, v82, v163, v102
	v_fma_f32 v83, v83, v163, v228
	v_fma_f32 v84, v84, v163, v103
	v_fma_f32 v85, v85, v163, v229
	v_fma_f32 v74, v74, v163, v104
	v_fma_f32 v75, v75, v163, v230
	v_fma_f32 v76, v76, v163, v105
	v_fma_f32 v77, v77, v163, v231
	v_cvt_pk_bf16_f32 v82, v82, v83
	v_cvt_pk_bf16_f32 v83, v84, v85
	v_cvt_pk_bf16_f32 v84, v74, v75
	v_cvt_pk_bf16_f32 v85, v76, v77
	v_permlane16_swap_b32_e32 v70, v66
	v_permlane16_swap_b32_e32 v71, v67
	v_permlane16_swap_b32_e32 v72, v68
	v_permlane16_swap_b32_e32 v73, v69
	v_cvt_f32_i32_e32 v70, v70
	v_cvt_f32_i32_e32 v71, v71
	v_cvt_f32_i32_e32 v72, v72
	v_cvt_f32_i32_e32 v73, v73
	v_cvt_f32_i32_e32 v66, v66
	v_cvt_f32_i32_e32 v67, v67
	v_cvt_f32_i32_e32 v68, v68
	v_cvt_f32_i32_e32 v69, v69
	s_waitcnt vmcnt(0)
; __device__ __forceinline__ unsigned cvt_pk_bf16(float lo, float hi) { unsigned r; asm("v_cvt_pk_bf16_f32 %0, %1, %2" : "=v"(r) : "v"(lo), "v"(hi)); return r; }
; __device__ __forceinline__ f32x4 ld_bf4(const bf16_t* p) { const u32x2 w = *(const u32x2*)p; return (f32x4){bf_lo(w.x), bf_hi(w.x), bf_lo(w.y), bf_hi(w.y)}; }
;     __device__ __forceinline__ void operator()(const f32x4 (&acc)[2][2][4][2], const pg8::Unit& u, int wr, int wc, int fr, int fq) const {
;         const int row0 = u.pm * 256 + wr * 64 + fr, col0 = u.pn * 256 + wc * 32 + 4 * fq;
;         f32x4 swv[2][2];
; #pragma unroll
;         for (int bj = 0; bj < 2; ++bj)
; #pragma unroll
;             for (int n = 0; n < 2; ++n) swv[bj][n] = *(const f32x4*)(sw + col0 + bj * 128 + n * 16);
;         float sav[2][4];
; #pragma unroll
;         for (int ai = 0; ai < 2; ++ai)
; #pragma unroll
;             for (int m = 0; m < 4; ++m) sav[ai][m] = sa[row0 + ai * 128 + m * 16];
; #pragma unroll
;         for (int am = 0; am < 4; ++am) { const int ai = am >> 1, m0 = 2 * (am & 1); f32x4 r[2][2][2];
; #pragma unroll
;             for (int mm = 0; mm < 2; ++mm) { const size_t off = (size_t)(row0 + ai * 128 + (m0 + mm) * 16) * DM + col0;
; #pragma unroll
;                 for (int bj = 0; bj < 2; ++bj)
; #pragma unroll
;                     for (int n = 0; n < 2; ++n) r[mm][bj][n] = ld_bf4(X1 + off + bj * 128 + n * 16); }
; #pragma unroll
;             for (int mm = 0; mm < 2; ++mm) { const size_t off = (size_t)(row0 + ai * 128 + (m0 + mm) * 16) * DM + col0;
; #pragma unroll
;                 for (int bj = 0; bj < 2; ++bj)
; #pragma unroll
;                     for (int n = 0; n < 2; ++n) { const i32x4 q = __builtin_bit_cast(i32x4, acc[ai][bj][m0 + mm][n]);
;                         const f32x4 v = (f32x4){(float)q[0], (float)q[1], (float)q[2], (float)q[3]} * swv[bj][n] * sav[ai][m0 + mm] + r[mm][bj][n];
;                         u32x2 w; w.x = cvt_pk_bf16(v[0], v[1]); w.y = cvt_pk_bf16(v[2], v[3]); *(u32x2*)(X2 + off + bj * 128 + n * 16) = w; } } }
;     }
	v_pk_mul_f32 v[70:71], v[70:71], v[192:193]
	v_pk_mul_f32 v[72:73], v[72:73], v[194:195]
	v_pk_mul_f32 v[66:67], v[66:67], v[196:197]
	v_pk_mul_f32 v[68:69], v[68:69], v[198:199]
	v_lshlrev_b32_e32 v102, 16, v98
	v_and_b32_e32 v98, 0xffff0000, v98
	v_lshlrev_b32_e32 v103, 16, v99
	v_and_b32_e32 v99, 0xffff0000, v99
	v_lshlrev_b32_e32 v104, 16, v100
	v_and_b32_e32 v100, 0xffff0000, v100
	v_lshlrev_b32_e32 v105, 16, v101
	v_and_b32_e32 v101, 0xffff0000, v101
	v_fma_f32 v70, v70, v163, v102
	v_fma_f32 v71, v71, v163, v98
	v_fma_f32 v72, v72, v163, v103
	v_fma_f32 v73, v73, v163, v99
	v_fma_f32 v66, v66, v163, v104
	v_fma_f32 v67, v67, v163, v100
	v_fma_f32 v68, v68, v163, v105
	v_fma_f32 v69, v69, v163, v101
	v_cvt_pk_bf16_f32 v70, v70, v71
	v_cvt_pk_bf16_f32 v71, v72, v73
	v_cvt_pk_bf16_f32 v72, v66, v67
	v_cvt_pk_bf16_f32 v73, v68, v69
	v_add_u32_e32 v156, 0x100000, v154
	global_load_dwordx4 v[138:141], v156, s[16:17] offset:0
	v_add_u32_e32 v157, 0x100000, v154
	global_load_dwordx4 v[126:129], v157, s[16:17] offset:256
	v_add_u32_e32 v156, 0x120000, v154
	global_load_dwordx4 v[122:125], v156, s[16:17] offset:0
	v_add_u32_e32 v157, 0x120000, v154
	global_load_dwordx4 v[114:117], v157, s[16:17] offset:256
	v_add_u32_e32 v156, 0x140000, v154
	global_load_dwordx4 v[106:109], v156, s[16:17] offset:0
	v_add_u32_e32 v157, 0x140000, v154
	global_load_dwordx4 v[78:81], v157, s[16:17] offset:256
	v_add_u32_e32 v156, 0x160000, v154
	global_load_dwordx4 v[74:77], v156, s[16:17] offset:0
	v_add_u32_e32 v157, 0x160000, v154
	global_load_dwordx4 v[66:69], v157, s[16:17] offset:256
	v_mov_b32_e32 v156, v154
	global_store_dwordx4 v156, v[94:97], s[18:19] offset:0
	v_mov_b32_e32 v157, v154
	global_store_dwordx4 v157, v[134:137], s[18:19] offset:256
	v_add_u32_e32 v156, 0x20000, v154
	global_store_dwordx4 v156, v[130:133], s[18:19] offset:0
	v_add_u32_e32 v157, 0x20000, v154
	global_store_dwordx4 v157, v[118:121], s[18:19] offset:256
	v_add_u32_e32 v156, 0x40000, v154
	global_store_dwordx4 v156, v[110:113], s[18:19] offset:0
	v_add_u32_e32 v157, 0x40000, v154
	global_store_dwordx4 v157, v[86:89], s[18:19] offset:256
	v_add_u32_e32 v156, 0x60000, v154
	global_store_dwordx4 v156, v[82:85], s[18:19] offset:0
	v_add_u32_e32 v157, 0x60000, v154
	global_store_dwordx4 v157, v[70:73], s[18:19] offset:256
	v_permlane16_swap_b32_e32 v62, v58
	v_permlane16_swap_b32_e32 v63, v59
	v_permlane16_swap_b32_e32 v64, v60
	v_permlane16_swap_b32_e32 v65, v61
	v_cvt_f32_i32_e32 v62, v62
	v_cvt_f32_i32_e32 v63, v63
	v_cvt_f32_i32_e32 v64, v64
	v_cvt_f32_i32_e32 v65, v65
	v_cvt_f32_i32_e32 v58, v58
	v_cvt_f32_i32_e32 v59, v59
	v_cvt_f32_i32_e32 v60, v60
	v_cvt_f32_i32_e32 v61, v61
	s_waitcnt vmcnt(15)
	v_pk_mul_f32 v[62:63], v[62:63], v[184:185]
	v_pk_mul_f32 v[64:65], v[64:65], v[186:187]
	v_pk_mul_f32 v[58:59], v[58:59], v[188:189]
	v_pk_mul_f32 v[60:61], v[60:61], v[190:191]
	v_lshlrev_b32_e32 v102, 16, v138
	v_and_b32_e32 v138, 0xffff0000, v138
	v_lshlrev_b32_e32 v103, 16, v139
	v_and_b32_e32 v139, 0xffff0000, v139
	v_lshlrev_b32_e32 v104, 16, v140
	v_and_b32_e32 v140, 0xffff0000, v140
	v_lshlrev_b32_e32 v105, 16, v141
	v_and_b32_e32 v141, 0xffff0000, v141
	v_fma_f32 v62, v62, v164, v102
	v_fma_f32 v63, v63, v164, v138
	v_fma_f32 v64, v64, v164, v103
	v_fma_f32 v65, v65, v164, v139
	v_fma_f32 v58, v58, v164, v104
	v_fma_f32 v59, v59, v164, v140
	v_fma_f32 v60, v60, v164, v105
	v_fma_f32 v61, v61, v164, v141
	v_cvt_pk_bf16_f32 v62, v62, v63
	v_cvt_pk_bf16_f32 v63, v64, v65
	v_cvt_pk_bf16_f32 v64, v58, v59
	v_cvt_pk_bf16_f32 v65, v60, v61
	v_add_u32_e32 v156, 0x100000, v154
	global_store_dwordx4 v156, v[62:65], s[18:19] offset:0
	v_permlane16_swap_b32_e32 v54, v46
	v_permlane16_swap_b32_e32 v55, v47
	v_permlane16_swap_b32_e32 v56, v48
	v_permlane16_swap_b32_e32 v57, v49
	v_cvt_f32_i32_e32 v54, v54
	v_cvt_f32_i32_e32 v55, v55
	v_cvt_f32_i32_e32 v56, v56
	v_cvt_f32_i32_e32 v57, v57
	v_cvt_f32_i32_e32 v46, v46
	v_cvt_f32_i32_e32 v47, v47
	v_cvt_f32_i32_e32 v48, v48
	v_cvt_f32_i32_e32 v49, v49
	s_waitcnt vmcnt(15)
	v_pk_mul_f32 v[54:55], v[54:55], v[192:193]
	v_pk_mul_f32 v[56:57], v[56:57], v[194:195]
	v_pk_mul_f32 v[46:47], v[46:47], v[196:197]
	v_pk_mul_f32 v[48:49], v[48:49], v[198:199]
	v_lshlrev_b32_e32 v102, 16, v126
	v_and_b32_e32 v126, 0xffff0000, v126
	v_lshlrev_b32_e32 v103, 16, v127
	v_and_b32_e32 v127, 0xffff0000, v127
	v_lshlrev_b32_e32 v104, 16, v128
	v_and_b32_e32 v128, 0xffff0000, v128
	v_lshlrev_b32_e32 v105, 16, v129
	v_and_b32_e32 v129, 0xffff0000, v129
	v_fma_f32 v54, v54, v164, v102
	v_fma_f32 v55, v55, v164, v126
	v_fma_f32 v56, v56, v164, v103
	v_fma_f32 v57, v57, v164, v127
	v_fma_f32 v46, v46, v164, v104
	v_fma_f32 v47, v47, v164, v128
	v_fma_f32 v48, v48, v164, v105
	v_fma_f32 v49, v49, v164, v129
	v_cvt_pk_bf16_f32 v54, v54, v55
	v_cvt_pk_bf16_f32 v55, v56, v57
	v_cvt_pk_bf16_f32 v56, v46, v47
	v_cvt_pk_bf16_f32 v57, v48, v49
	v_add_u32_e32 v157, 0x100000, v154
	global_store_dwordx4 v157, v[54:57], s[18:19] offset:256
	v_permlane16_swap_b32_e32 v50, v42
	v_permlane16_swap_b32_e32 v51, v43
	v_permlane16_swap_b32_e32 v52, v44
	v_permlane16_swap_b32_e32 v53, v45
	v_cvt_f32_i32_e32 v50, v50
	v_cvt_f32_i32_e32 v51, v51
	v_cvt_f32_i32_e32 v52, v52
	v_cvt_f32_i32_e32 v53, v53
	v_cvt_f32_i32_e32 v42, v42
	v_cvt_f32_i32_e32 v43, v43
	v_cvt_f32_i32_e32 v44, v44
	v_cvt_f32_i32_e32 v45, v45
	s_waitcnt vmcnt(15)
; __device__ __forceinline__ unsigned cvt_pk_bf16(float lo, float hi) { unsigned r; asm("v_cvt_pk_bf16_f32 %0, %1, %2" : "=v"(r) : "v"(lo), "v"(hi)); return r; }
; __device__ __forceinline__ f32x4 ld_bf4(const bf16_t* p) { const u32x2 w = *(const u32x2*)p; return (f32x4){bf_lo(w.x), bf_hi(w.x), bf_lo(w.y), bf_hi(w.y)}; }
;     __device__ __forceinline__ void operator()(const f32x4 (&acc)[2][2][4][2], const pg8::Unit& u, int wr, int wc, int fr, int fq) const {
;         const int row0 = u.pm * 256 + wr * 64 + fr, col0 = u.pn * 256 + wc * 32 + 4 * fq;
;         f32x4 swv[2][2];
; #pragma unroll
;         for (int bj = 0; bj < 2; ++bj)
; #pragma unroll
;             for (int n = 0; n < 2; ++n) swv[bj][n] = *(const f32x4*)(sw + col0 + bj * 128 + n * 16);
;         float sav[2][4];
; #pragma unroll
;         for (int ai = 0; ai < 2; ++ai)
; #pragma unroll
;             for (int m = 0; m < 4; ++m) sav[ai][m] = sa[row0 + ai * 128 + m * 16];
; #pragma unroll
;         for (int am = 0; am < 4; ++am) { const int ai = am >> 1, m0 = 2 * (am & 1); f32x4 r[2][2][2];
; #pragma unroll
;             for (int mm = 0; mm < 2; ++mm) { const size_t off = (size_t)(row0 + ai * 128 + (m0 + mm) * 16) * DM + col0;
; #pragma unroll
;                 for (int bj = 0; bj < 2; ++bj)
; #pragma unroll
;                     for (int n = 0; n < 2; ++n) r[mm][bj][n] = ld_bf4(X1 + off + bj * 128 + n * 16); }
; #pragma unroll
;             for (int mm = 0; mm < 2; ++mm) { const size_t off = (size_t)(row0 + ai * 128 + (m0 + mm) * 16) * DM + col0;
; #pragma unroll
;                 for (int bj = 0; bj < 2; ++bj)
; #pragma unroll
;                     for (int n = 0; n < 2; ++n) { const i32x4 q = __builtin_bit_cast(i32x4, acc[ai][bj][m0 + mm][n]);
;                         const f32x4 v = (f32x4){(float)q[0], (float)q[1], (float)q[2], (float)q[3]} * swv[bj][n] * sav[ai][m0 + mm] + r[mm][bj][n];
;                         u32x2 w; w.x = cvt_pk_bf16(v[0], v[1]); w.y = cvt_pk_bf16(v[2], v[3]); *(u32x2*)(X2 + off + bj * 128 + n * 16) = w; } } }
;     }
	v_pk_mul_f32 v[50:51], v[50:51], v[184:185]
	v_pk_mul_f32 v[52:53], v[52:53], v[186:187]
	v_pk_mul_f32 v[42:43], v[42:43], v[188:189]
	v_pk_mul_f32 v[44:45], v[44:45], v[190:191]
	v_lshlrev_b32_e32 v102, 16, v122
	v_and_b32_e32 v122, 0xffff0000, v122
	v_lshlrev_b32_e32 v103, 16, v123
	v_and_b32_e32 v123, 0xffff0000, v123
	v_lshlrev_b32_e32 v104, 16, v124
	v_and_b32_e32 v124, 0xffff0000, v124
	v_lshlrev_b32_e32 v105, 16, v125
	v_and_b32_e32 v125, 0xffff0000, v125
	v_fma_f32 v50, v50, v166, v102
	v_fma_f32 v51, v51, v166, v122
	v_fma_f32 v52, v52, v166, v103
	v_fma_f32 v53, v53, v166, v123
	v_fma_f32 v42, v42, v166, v104
	v_fma_f32 v43, v43, v166, v124
	v_fma_f32 v44, v44, v166, v105
	v_fma_f32 v45, v45, v166, v125
	v_cvt_pk_bf16_f32 v50, v50, v51
	v_cvt_pk_bf16_f32 v51, v52, v53
	v_cvt_pk_bf16_f32 v52, v42, v43
	v_cvt_pk_bf16_f32 v53, v44, v45
	v_add_u32_e32 v156, 0x120000, v154
	global_store_dwordx4 v156, v[50:53], s[18:19] offset:0
	v_permlane16_swap_b32_e32 v38, v34
	v_permlane16_swap_b32_e32 v39, v35
	v_permlane16_swap_b32_e32 v40, v36
	v_permlane16_swap_b32_e32 v41, v37
	v_cvt_f32_i32_e32 v38, v38
	v_cvt_f32_i32_e32 v39, v39
	v_cvt_f32_i32_e32 v40, v40
	v_cvt_f32_i32_e32 v41, v41
	v_cvt_f32_i32_e32 v34, v34
	v_cvt_f32_i32_e32 v35, v35
	v_cvt_f32_i32_e32 v36, v36
	v_cvt_f32_i32_e32 v37, v37
	s_waitcnt vmcnt(15)
	v_pk_mul_f32 v[38:39], v[38:39], v[192:193]
	v_pk_mul_f32 v[40:41], v[40:41], v[194:195]
	v_pk_mul_f32 v[34:35], v[34:35], v[196:197]
	v_pk_mul_f32 v[36:37], v[36:37], v[198:199]
	v_lshlrev_b32_e32 v102, 16, v114
	v_and_b32_e32 v114, 0xffff0000, v114
	v_lshlrev_b32_e32 v103, 16, v115
	v_and_b32_e32 v115, 0xffff0000, v115
	v_lshlrev_b32_e32 v104, 16, v116
	v_and_b32_e32 v116, 0xffff0000, v116
	v_lshlrev_b32_e32 v105, 16, v117
	v_and_b32_e32 v117, 0xffff0000, v117
	v_fma_f32 v38, v38, v166, v102
	v_fma_f32 v39, v39, v166, v114
	v_fma_f32 v40, v40, v166, v103
	v_fma_f32 v41, v41, v166, v115
	v_fma_f32 v34, v34, v166, v104
	v_fma_f32 v35, v35, v166, v116
	v_fma_f32 v36, v36, v166, v105
	v_fma_f32 v37, v37, v166, v117
	v_cvt_pk_bf16_f32 v38, v38, v39
	v_cvt_pk_bf16_f32 v39, v40, v41
	v_cvt_pk_bf16_f32 v40, v34, v35
	v_cvt_pk_bf16_f32 v41, v36, v37
	v_add_u32_e32 v157, 0x120000, v154
	global_store_dwordx4 v157, v[38:41], s[18:19] offset:256
	v_permlane16_swap_b32_e32 v30, v26
	v_permlane16_swap_b32_e32 v31, v27
	v_permlane16_swap_b32_e32 v32, v28
	v_permlane16_swap_b32_e32 v33, v29
	v_cvt_f32_i32_e32 v30, v30
	v_cvt_f32_i32_e32 v31, v31
	v_cvt_f32_i32_e32 v32, v32
	v_cvt_f32_i32_e32 v33, v33
	v_cvt_f32_i32_e32 v26, v26
	v_cvt_f32_i32_e32 v27, v27
	v_cvt_f32_i32_e32 v28, v28
	v_cvt_f32_i32_e32 v29, v29
	s_waitcnt vmcnt(15)
	v_pk_mul_f32 v[30:31], v[30:31], v[184:185]
	v_pk_mul_f32 v[32:33], v[32:33], v[186:187]
	v_pk_mul_f32 v[26:27], v[26:27], v[188:189]
	v_pk_mul_f32 v[28:29], v[28:29], v[190:191]
	v_lshlrev_b32_e32 v102, 16, v106
	v_and_b32_e32 v106, 0xffff0000, v106
	v_lshlrev_b32_e32 v103, 16, v107
	v_and_b32_e32 v107, 0xffff0000, v107
	v_lshlrev_b32_e32 v104, 16, v108
	v_and_b32_e32 v108, 0xffff0000, v108
	v_lshlrev_b32_e32 v105, 16, v109
	v_and_b32_e32 v109, 0xffff0000, v109
	v_fma_f32 v30, v30, v167, v102
	v_fma_f32 v31, v31, v167, v106
	v_fma_f32 v32, v32, v167, v103
	v_fma_f32 v33, v33, v167, v107
	v_fma_f32 v26, v26, v167, v104
	v_fma_f32 v27, v27, v167, v108
	v_fma_f32 v28, v28, v167, v105
	v_fma_f32 v29, v29, v167, v109
	v_cvt_pk_bf16_f32 v30, v30, v31
	v_cvt_pk_bf16_f32 v31, v32, v33
	v_cvt_pk_bf16_f32 v32, v26, v27
	v_cvt_pk_bf16_f32 v33, v28, v29
	v_add_u32_e32 v156, 0x140000, v154
	global_store_dwordx4 v156, v[30:33], s[18:19] offset:0
	v_permlane16_swap_b32_e32 v22, v14
	v_permlane16_swap_b32_e32 v23, v15
	v_permlane16_swap_b32_e32 v24, v16
	v_permlane16_swap_b32_e32 v25, v17
	v_cvt_f32_i32_e32 v22, v22
	v_cvt_f32_i32_e32 v23, v23
	v_cvt_f32_i32_e32 v24, v24
	v_cvt_f32_i32_e32 v25, v25
	v_cvt_f32_i32_e32 v14, v14
	v_cvt_f32_i32_e32 v15, v15
	v_cvt_f32_i32_e32 v16, v16
	v_cvt_f32_i32_e32 v17, v17
	s_waitcnt vmcnt(15)
; __device__ __forceinline__ unsigned cvt_pk_bf16(float lo, float hi) { unsigned r; asm("v_cvt_pk_bf16_f32 %0, %1, %2" : "=v"(r) : "v"(lo), "v"(hi)); return r; }
; __device__ __forceinline__ f32x4 ld_bf4(const bf16_t* p) { const u32x2 w = *(const u32x2*)p; return (f32x4){bf_lo(w.x), bf_hi(w.x), bf_lo(w.y), bf_hi(w.y)}; }
;     __device__ __forceinline__ void operator()(const f32x4 (&acc)[2][2][4][2], const pg8::Unit& u, int wr, int wc, int fr, int fq) const {
;         const int row0 = u.pm * 256 + wr * 64 + fr, col0 = u.pn * 256 + wc * 32 + 4 * fq;
;         f32x4 swv[2][2];
; #pragma unroll
;         for (int bj = 0; bj < 2; ++bj)
; #pragma unroll
;             for (int n = 0; n < 2; ++n) swv[bj][n] = *(const f32x4*)(sw + col0 + bj * 128 + n * 16);
;         float sav[2][4];
; #pragma unroll
;         for (int ai = 0; ai < 2; ++ai)
; #pragma unroll
;             for (int m = 0; m < 4; ++m) sav[ai][m] = sa[row0 + ai * 128 + m * 16];
; #pragma unroll
;         for (int am = 0; am < 4; ++am) { const int ai = am >> 1, m0 = 2 * (am & 1); f32x4 r[2][2][2];
; #pragma unroll
;             for (int mm = 0; mm < 2; ++mm) { const size_t off = (size_t)(row0 + ai * 128 + (m0 + mm) * 16) * DM + col0;
; #pragma unroll
;                 for (int bj = 0; bj < 2; ++bj)
; #pragma unroll
;                     for (int n = 0; n < 2; ++n) r[mm][bj][n] = ld_bf4(X1 + off + bj * 128 + n * 16); }
; #pragma unroll
;             for (int mm = 0; mm < 2; ++mm) { const size_t off = (size_t)(row0 + ai * 128 + (m0 + mm) * 16) * DM + col0;
; #pragma unroll
;                 for (int bj = 0; bj < 2; ++bj)
; #pragma unroll
;                     for (int n = 0; n < 2; ++n) { const i32x4 q = __builtin_bit_cast(i32x4, acc[ai][bj][m0 + mm][n]);
;                         const f32x4 v = (f32x4){(float)q[0], (float)q[1], (float)q[2], (float)q[3]} * swv[bj][n] * sav[ai][m0 + mm] + r[mm][bj][n];
;                         u32x2 w; w.x = cvt_pk_bf16(v[0], v[1]); w.y = cvt_pk_bf16(v[2], v[3]); *(u32x2*)(X2 + off + bj * 128 + n * 16) = w; } } }
;     }
	v_pk_mul_f32 v[22:23], v[22:23], v[192:193]
	v_pk_mul_f32 v[24:25], v[24:25], v[194:195]
	v_pk_mul_f32 v[14:15], v[14:15], v[196:197]
	v_pk_mul_f32 v[16:17], v[16:17], v[198:199]
	v_lshlrev_b32_e32 v102, 16, v78
	v_and_b32_e32 v78, 0xffff0000, v78
	v_lshlrev_b32_e32 v103, 16, v79
	v_and_b32_e32 v79, 0xffff0000, v79
	v_lshlrev_b32_e32 v104, 16, v80
	v_and_b32_e32 v80, 0xffff0000, v80
	v_lshlrev_b32_e32 v105, 16, v81
	v_and_b32_e32 v81, 0xffff0000, v81
	v_fma_f32 v22, v22, v167, v102
	v_fma_f32 v23, v23, v167, v78
	v_fma_f32 v24, v24, v167, v103
	v_fma_f32 v25, v25, v167, v79
	v_fma_f32 v14, v14, v167, v104
	v_fma_f32 v15, v15, v167, v80
	v_fma_f32 v16, v16, v167, v105
	v_fma_f32 v17, v17, v167, v81
	v_cvt_pk_bf16_f32 v22, v22, v23
	v_cvt_pk_bf16_f32 v23, v24, v25
	v_cvt_pk_bf16_f32 v24, v14, v15
	v_cvt_pk_bf16_f32 v25, v16, v17
	v_add_u32_e32 v157, 0x140000, v154
	global_store_dwordx4 v157, v[22:25], s[18:19] offset:256
	v_permlane16_swap_b32_e32 v18, v10
	v_permlane16_swap_b32_e32 v19, v11
	v_permlane16_swap_b32_e32 v20, v12
	v_permlane16_swap_b32_e32 v21, v13
	v_cvt_f32_i32_e32 v18, v18
	v_cvt_f32_i32_e32 v19, v19
	v_cvt_f32_i32_e32 v20, v20
	v_cvt_f32_i32_e32 v21, v21
	v_cvt_f32_i32_e32 v10, v10
	v_cvt_f32_i32_e32 v11, v11
	v_cvt_f32_i32_e32 v12, v12
	v_cvt_f32_i32_e32 v13, v13
	s_waitcnt vmcnt(15)
	v_pk_mul_f32 v[18:19], v[18:19], v[184:185]
	v_pk_mul_f32 v[20:21], v[20:21], v[186:187]
	v_pk_mul_f32 v[10:11], v[10:11], v[188:189]
	v_pk_mul_f32 v[12:13], v[12:13], v[190:191]
	v_lshlrev_b32_e32 v102, 16, v74
	v_and_b32_e32 v74, 0xffff0000, v74
	v_lshlrev_b32_e32 v103, 16, v75
	v_and_b32_e32 v75, 0xffff0000, v75
	v_lshlrev_b32_e32 v104, 16, v76
	v_and_b32_e32 v76, 0xffff0000, v76
	v_lshlrev_b32_e32 v105, 16, v77
	v_and_b32_e32 v77, 0xffff0000, v77
	v_fma_f32 v18, v18, v168, v102
	v_fma_f32 v19, v19, v168, v74
	v_fma_f32 v20, v20, v168, v103
	v_fma_f32 v21, v21, v168, v75
	v_fma_f32 v10, v10, v168, v104
	v_fma_f32 v11, v11, v168, v76
	v_fma_f32 v12, v12, v168, v105
	v_fma_f32 v13, v13, v168, v77
	v_cvt_pk_bf16_f32 v18, v18, v19
	v_cvt_pk_bf16_f32 v19, v20, v21
	v_cvt_pk_bf16_f32 v20, v10, v11
	v_cvt_pk_bf16_f32 v21, v12, v13
	v_add_u32_e32 v156, 0x160000, v154
	global_store_dwordx4 v156, v[18:21], s[18:19] offset:0
	v_permlane16_swap_b32_e32 v6, v2
	v_permlane16_swap_b32_e32 v7, v3
	v_permlane16_swap_b32_e32 v8, v4
	v_permlane16_swap_b32_e32 v9, v5
	v_cvt_f32_i32_e32 v6, v6
	v_cvt_f32_i32_e32 v7, v7
	v_cvt_f32_i32_e32 v8, v8
	v_cvt_f32_i32_e32 v9, v9
	v_cvt_f32_i32_e32 v2, v2
	v_cvt_f32_i32_e32 v3, v3
	v_cvt_f32_i32_e32 v4, v4
	v_cvt_f32_i32_e32 v5, v5
	s_waitcnt vmcnt(15)
	v_pk_mul_f32 v[6:7], v[6:7], v[192:193]
	v_pk_mul_f32 v[8:9], v[8:9], v[194:195]
	v_pk_mul_f32 v[2:3], v[2:3], v[196:197]
	v_pk_mul_f32 v[4:5], v[4:5], v[198:199]
	v_lshlrev_b32_e32 v102, 16, v66
	v_and_b32_e32 v66, 0xffff0000, v66
	v_lshlrev_b32_e32 v103, 16, v67
	v_and_b32_e32 v67, 0xffff0000, v67
	v_lshlrev_b32_e32 v104, 16, v68
	v_and_b32_e32 v68, 0xffff0000, v68
	v_lshlrev_b32_e32 v105, 16, v69
	v_and_b32_e32 v69, 0xffff0000, v69
	v_fma_f32 v6, v6, v168, v102
	v_fma_f32 v7, v7, v168, v66
	v_fma_f32 v8, v8, v168, v103
	v_fma_f32 v9, v9, v168, v67
	v_fma_f32 v2, v2, v168, v104
	v_fma_f32 v3, v3, v168, v68
	v_fma_f32 v4, v4, v168, v105
	v_fma_f32 v5, v5, v168, v69
	v_cvt_pk_bf16_f32 v6, v6, v7
	v_cvt_pk_bf16_f32 v7, v8, v9
	v_cvt_pk_bf16_f32 v8, v2, v3
	v_cvt_pk_bf16_f32 v9, v4, v5
	v_add_u32_e32 v157, 0x160000, v154
	global_store_dwordx4 v157, v[6:9], s[18:19] offset:256
	s_and_b64 vcc, exec, s[4:5]
	s_mov_b64 s[4:5], -1
	s_cbranch_vccnz .LBB0_2864
	s_andn2_b64 vcc, exec, s[2:3]
	s_cbranch_vccnz .LBB0_2863
	s_barrier
	s_branch .LBB0_2863
